# P1 rope epilogues (EpiZ types 0/1) rewritten by hand: table loads of the 8 row groups prefetched 3 groups ahead into 4 register sets, counted vmcnt instead of vmcnt(0) per group
# speedup vs baseline: 1.0054x; 1.0054x over previous
;     template <int TYPE> __device__ __forceinline__ void run(const Acc& acc, const Unit& u, int wr, int wc, int fr, int fq) const {
;     ...
;         for (int ai = 0; ai < 2; ++ai)
; #pragma unroll
;             for (int m = 0; m < 4; ++m) {
;                 const int row = u.pm * 256 + ai * 128 + wr * 64 + m * 16 + fr;
;                 float v[2][8];
; #pragma unroll
;                 for (int bj = 0; bj < 2; ++bj)
; #pragma unroll
;                     for (int n = 0; n < 2; ++n)
; #pragma unroll
;                         for (int i = 0; i < 4; ++i) v[bj][4 * n + i] = acc[ai][bj][m][n][i];
;                 if (TYPE == 0 || TYPE == 1) {
;                     const int pos = row & (SEQ - 1);
;                     const f32x4* tp = (const f32x4*)(tab + ((size_t)pos * 32 + 8 * fq) * 2);
;                     const float lgp = lg2gamma(((u.pn & 1) << 2) + wc) * (float)pos;
;                     const float sc = (TYPE == 1) ? 0.125f * __builtin_amdgcn_exp2f(-lgp) : __builtin_amdgcn_exp2f(lgp);
; #pragma unroll
;                     for (int jj = 0; jj < 4; ++jj) { const f32x4 cs = tp[jj];
;                         { const float t1 = v[0][2 * jj], t2 = v[1][2 * jj]; v[0][2 * jj] = (t1 * cs.x - t2 * cs.y) * sc; v[1][2 * jj] = (t1 * cs.y + t2 * cs.x) * sc; }
;                         { const float t1 = v[0][2 * jj + 1], t2 = v[1][2 * jj + 1]; v[0][2 * jj + 1] = (t1 * cs.z - t2 * cs.w) * sc; v[1][2 * jj + 1] = (t1 * cs.w + t2 * cs.z) * sc; } }
;                 }
;                 if (TYPE == 3) {
; #pragma unroll
;                     for (int bj = 0; bj < 2; ++bj)
; #pragma unroll
;                         for (int j = 0; j < 8; ++j) { const float x = v[bj][j]; v[bj][j] = x * __builtin_amdgcn_rcpf(1.0f + __builtin_amdgcn_exp2f(-1.4426950408889634f * x)); }
;                 }
;                 if (TYPE == 4 || TYPE == 5) {
;                     float ss = 0.f;
; #pragma unroll
;                     for (int bj = 0; bj < 2; ++bj)
; #pragma unroll
;                         for (int j = 0; j < 8; ++j) ss += v[bj][j] * v[bj][j];
;                     ss = quad_sum(ss);
;                     const float r = rsqrtf(ss * (1.0f / 64.0f) + EPS);
; #pragma unroll
;                     for (int bj = 0; bj < 2; ++bj)
; #pragma unroll
;                         for (int j = 0; j < 8; ++j) v[bj][j] = v[bj][j] * r * g[bj][j];
;                 }
.LBB0_131:
	s_andn2_b64 vcc, exec, s[2:3]
	s_cbranch_vccnz .LBB0_301
	s_lshl_b32 s2, s44, 2
	s_and_b32 s2, s2, 4
	s_or_b32 s6, s2, s31
	s_mov_b32 s2, 0xbd3b9ca6
	s_cmp_eq_u32 s6, 1
	s_cselect_b32 s2, 0xbcba1f74, s2
	s_cmp_eq_u32 s6, 2
	s_cselect_b32 s2, 0xbc3963dd, s2
	s_cmp_eq_u32 s6, 3
	s_cselect_b32 s2, 0xbbb906ce, s2
	s_cmp_eq_u32 s6, 4
	s_cselect_b32 s2, 0xbb38d875, s2
	s_cmp_eq_u32 s6, 5
	s_cselect_b32 s2, 0xbab8c154, s2
	s_cmp_eq_u32 s6, 6
	s_cselect_b32 s2, 0xba38b5c7, s2
	s_cmp_eq_u32 s6, 7
	s_cselect_b32 s2, 0xb9b8b001, s2
	s_xor_b32 s2, s2, 0x80000000
	s_lshl_b32 s3, s46, 8
	s_add_i32 s3, s3, s79
	v_add_u32_e32 v130, s3, v209
	v_and_b32_e32 v159, 0x7ff, v130
	v_lshlrev_b32_e32 v128, 8, v159
	v_lshl_add_u32 v128, v210, 6, v128
	v_mov_b32_e32 v244, v128
	global_load_dwordx4 v[132:135], v244, s[26:27]
	global_load_dwordx4 v[136:139], v244, s[26:27] offset:16
	global_load_dwordx4 v[140:143], v244, s[26:27] offset:32
	global_load_dwordx4 v[164:167], v244, s[26:27] offset:48
	v_add_u32_e32 v245, 0x1000, v128
	global_load_dwordx4 v[212:215], v245, s[26:27]
	global_load_dwordx4 v[216:219], v245, s[26:27] offset:16
	global_load_dwordx4 v[220:223], v245, s[26:27] offset:32
	global_load_dwordx4 v[224:227], v245, s[26:27] offset:48
	v_add_u32_e32 v246, 0x2000, v128
	global_load_dwordx4 v[228:231], v246, s[26:27]
	global_load_dwordx4 v[232:235], v246, s[26:27] offset:16
	global_load_dwordx4 v[236:239], v246, s[26:27] offset:32
	global_load_dwordx4 v[240:243], v246, s[26:27] offset:48
	v_add_u32_e32 v247, 0x3000, v128
	global_load_dwordx4 v[186:189], v247, s[26:27]
	global_load_dwordx4 v[190:193], v247, s[26:27] offset:16
	global_load_dwordx4 v[194:197], v247, s[26:27] offset:32
	global_load_dwordx4 v[198:201], v247, s[26:27] offset:48
	v_cvt_f32_u32_e32 v129, v159
	s_lshl_b32 s3, s44, 8
	s_or_b32 s3, s3, s86
	v_lshl_add_u32 v162, v210, 3, s3
	v_mul_u32_u24_e32 v131, 0x3800, v130
	v_lshl_add_u32 v131, v162, 1, v131
	v_mov_b32_e32 v152, v129
	v_mul_f32_e32 v152, s2, v152
	v_exp_f32_e32 v152, v152
	s_nop 0
	v_mul_f32_e32 v152, 0x3e000000, v152
	v_mov_b32_e32 v168, v131
	s_waitcnt vmcnt(12)
	v_mov_b32_e32 v170, v132
	v_mov_b32_e32 v171, v134
	v_mov_b32_e32 v172, v133
	v_mov_b32_e32 v173, v135
	v_mov_b32_e32 v174, v136
	v_mov_b32_e32 v175, v138
	v_mov_b32_e32 v176, v137
	v_mov_b32_e32 v177, v139
	v_mov_b32_e32 v178, v140
	v_mov_b32_e32 v179, v142
	v_mov_b32_e32 v180, v141
	v_mov_b32_e32 v181, v143
	v_mov_b32_e32 v182, v164
	v_mov_b32_e32 v183, v166
	v_mov_b32_e32 v248, v165
	v_mov_b32_e32 v249, v167
	v_pk_mul_f32 v[132:133], v[116:117], v[172:173]
	v_pk_mul_f32 v[134:135], v[116:117], v[170:171]
	v_pk_mul_f32 v[136:137], v[118:119], v[176:177]
	v_pk_mul_f32 v[138:139], v[118:119], v[174:175]
	v_pk_mul_f32 v[140:141], v[112:113], v[180:181]
	v_pk_mul_f32 v[142:143], v[112:113], v[178:179]
	v_pk_mul_f32 v[164:165], v[114:115], v[248:249]
	v_pk_mul_f32 v[166:167], v[114:115], v[182:183]
	v_pk_fma_f32 v[132:133], v[124:125], v[170:171], v[132:133] neg_lo:[0,0,1] neg_hi:[0,0,1]
	v_pk_fma_f32 v[134:135], v[124:125], v[172:173], v[134:135]
	v_pk_fma_f32 v[136:137], v[126:127], v[174:175], v[136:137] neg_lo:[0,0,1] neg_hi:[0,0,1]
	v_pk_fma_f32 v[138:139], v[126:127], v[176:177], v[138:139]
	v_pk_fma_f32 v[140:141], v[120:121], v[178:179], v[140:141] neg_lo:[0,0,1] neg_hi:[0,0,1]
	v_pk_fma_f32 v[142:143], v[120:121], v[180:181], v[142:143]
	v_pk_fma_f32 v[164:165], v[122:123], v[182:183], v[164:165] neg_lo:[0,0,1] neg_hi:[0,0,1]
	v_pk_fma_f32 v[166:167], v[122:123], v[248:249], v[166:167]
	v_pk_mul_f32 v[132:133], v[152:153], v[132:133] op_sel_hi:[0,1]
	v_pk_mul_f32 v[134:135], v[152:153], v[134:135] op_sel_hi:[0,1]
	v_pk_mul_f32 v[136:137], v[152:153], v[136:137] op_sel_hi:[0,1]
	v_pk_mul_f32 v[138:139], v[152:153], v[138:139] op_sel_hi:[0,1]
	v_pk_mul_f32 v[140:141], v[152:153], v[140:141] op_sel_hi:[0,1]
	v_pk_mul_f32 v[142:143], v[152:153], v[142:143] op_sel_hi:[0,1]
	v_pk_mul_f32 v[164:165], v[152:153], v[164:165] op_sel_hi:[0,1]
	v_pk_mul_f32 v[166:167], v[152:153], v[166:167] op_sel_hi:[0,1]
	v_cvt_pk_bf16_f32 v170, v132, v133
	v_cvt_pk_bf16_f32 v171, v136, v137
	v_cvt_pk_bf16_f32 v172, v140, v141
	v_cvt_pk_bf16_f32 v173, v164, v165
	v_cvt_pk_bf16_f32 v174, v134, v135
	v_cvt_pk_bf16_f32 v175, v138, v139
	v_cvt_pk_bf16_f32 v176, v142, v143
	v_cvt_pk_bf16_f32 v177, v166, v167
	global_store_dwordx4 v168, v[170:173], s[22:23]
	global_store_dwordx4 v168, v[174:177], s[22:23] offset:64
	v_add_u32_e32 v244, 0x8000, v128
	global_load_dwordx4 v[132:135], v244, s[26:27]
	global_load_dwordx4 v[136:139], v244, s[26:27] offset:16
	global_load_dwordx4 v[140:143], v244, s[26:27] offset:32
	global_load_dwordx4 v[164:167], v244, s[26:27] offset:48
	v_add_f32_e32 v152, 0x41800000, v129
	v_mul_f32_e32 v152, s2, v152
	v_exp_f32_e32 v152, v152
	s_nop 0
	v_mul_f32_e32 v152, 0x3e000000, v152
	v_add_u32_e32 v169, 0x38000, v131
	s_waitcnt vmcnt(12)
; __device__ __forceinline__ u32x4 pack8(const float (&v)[8]) { u32x4 w; w.x = cvtpk(v[0], v[1]); w.y = cvtpk(v[2], v[3]); w.z = cvtpk(v[4], v[5]); w.w = cvtpk(v[6], v[7]); return w; }
;     template <int TYPE> __device__ __forceinline__ void run(const Acc& acc, const Unit& u, int wr, int wc, int fr, int fq) const {
;     ...
;                 if (TYPE == 0 || TYPE == 1) {
;                     const int pos = row & (SEQ - 1);
;                     const f32x4* tp = (const f32x4*)(tab + ((size_t)pos * 32 + 8 * fq) * 2);
;                     const float lgp = lg2gamma(((u.pn & 1) << 2) + wc) * (float)pos;
;                     const float sc = (TYPE == 1) ? 0.125f * __builtin_amdgcn_exp2f(-lgp) : __builtin_amdgcn_exp2f(lgp);
; #pragma unroll
;                     for (int jj = 0; jj < 4; ++jj) { const f32x4 cs = tp[jj];
;                         { const float t1 = v[0][2 * jj], t2 = v[1][2 * jj]; v[0][2 * jj] = (t1 * cs.x - t2 * cs.y) * sc; v[1][2 * jj] = (t1 * cs.y + t2 * cs.x) * sc; }
;                         { const float t1 = v[0][2 * jj + 1], t2 = v[1][2 * jj + 1]; v[0][2 * jj + 1] = (t1 * cs.z - t2 * cs.w) * sc; v[1][2 * jj + 1] = (t1 * cs.w + t2 * cs.z) * sc; } }
;                 }
;                 if (TYPE == 3) {
; #pragma unroll
;                     for (int bj = 0; bj < 2; ++bj)
; #pragma unroll
;                         for (int j = 0; j < 8; ++j) { const float x = v[bj][j]; v[bj][j] = x * __builtin_amdgcn_rcpf(1.0f + __builtin_amdgcn_exp2f(-1.4426950408889634f * x)); }
;                 }
;                 if (TYPE == 4 || TYPE == 5) {
;                     float ss = 0.f;
; #pragma unroll
;                     for (int bj = 0; bj < 2; ++bj)
; #pragma unroll
;                         for (int j = 0; j < 8; ++j) ss += v[bj][j] * v[bj][j];
;                     ss = quad_sum(ss);
;                     const float r = rsqrtf(ss * (1.0f / 64.0f) + EPS);
; #pragma unroll
;                     for (int bj = 0; bj < 2; ++bj)
; #pragma unroll
;                         for (int j = 0; j < 8; ++j) v[bj][j] = v[bj][j] * r * g[bj][j];
;                 }
;                 bf16_t* rowp = Z + (size_t)row * DIN + colbase;
;                 *(u32x4*)(rowp) = pack8(v[0]); *(u32x4*)(rowp + 32) = pack8(v[1]);
	v_mov_b32_e32 v170, v212
	v_mov_b32_e32 v171, v214
	v_mov_b32_e32 v172, v213
	v_mov_b32_e32 v173, v215
	v_mov_b32_e32 v174, v216
	v_mov_b32_e32 v175, v218
	v_mov_b32_e32 v176, v217
	v_mov_b32_e32 v177, v219
	v_mov_b32_e32 v178, v220
	v_mov_b32_e32 v179, v222
	v_mov_b32_e32 v180, v221
	v_mov_b32_e32 v181, v223
	v_mov_b32_e32 v182, v224
	v_mov_b32_e32 v183, v226
	v_mov_b32_e32 v248, v225
	v_mov_b32_e32 v249, v227
	v_pk_mul_f32 v[212:213], v[100:101], v[172:173]
	v_pk_mul_f32 v[214:215], v[100:101], v[170:171]
	v_pk_mul_f32 v[216:217], v[102:103], v[176:177]
	v_pk_mul_f32 v[218:219], v[102:103], v[174:175]
	v_pk_mul_f32 v[220:221], v[96:97], v[180:181]
	v_pk_mul_f32 v[222:223], v[96:97], v[178:179]
	v_pk_mul_f32 v[224:225], v[98:99], v[248:249]
	v_pk_mul_f32 v[226:227], v[98:99], v[182:183]
	v_pk_fma_f32 v[212:213], v[108:109], v[170:171], v[212:213] neg_lo:[0,0,1] neg_hi:[0,0,1]
	v_pk_fma_f32 v[214:215], v[108:109], v[172:173], v[214:215]
	v_pk_fma_f32 v[216:217], v[110:111], v[174:175], v[216:217] neg_lo:[0,0,1] neg_hi:[0,0,1]
	v_pk_fma_f32 v[218:219], v[110:111], v[176:177], v[218:219]
	v_pk_fma_f32 v[220:221], v[104:105], v[178:179], v[220:221] neg_lo:[0,0,1] neg_hi:[0,0,1]
	v_pk_fma_f32 v[222:223], v[104:105], v[180:181], v[222:223]
	v_pk_fma_f32 v[224:225], v[106:107], v[182:183], v[224:225] neg_lo:[0,0,1] neg_hi:[0,0,1]
	v_pk_fma_f32 v[226:227], v[106:107], v[248:249], v[226:227]
	v_pk_mul_f32 v[212:213], v[152:153], v[212:213] op_sel_hi:[0,1]
	v_pk_mul_f32 v[214:215], v[152:153], v[214:215] op_sel_hi:[0,1]
	v_pk_mul_f32 v[216:217], v[152:153], v[216:217] op_sel_hi:[0,1]
	v_pk_mul_f32 v[218:219], v[152:153], v[218:219] op_sel_hi:[0,1]
	v_pk_mul_f32 v[220:221], v[152:153], v[220:221] op_sel_hi:[0,1]
	v_pk_mul_f32 v[222:223], v[152:153], v[222:223] op_sel_hi:[0,1]
	v_pk_mul_f32 v[224:225], v[152:153], v[224:225] op_sel_hi:[0,1]
	v_pk_mul_f32 v[226:227], v[152:153], v[226:227] op_sel_hi:[0,1]
	v_cvt_pk_bf16_f32 v170, v212, v213
	v_cvt_pk_bf16_f32 v171, v216, v217
	v_cvt_pk_bf16_f32 v172, v220, v221
	v_cvt_pk_bf16_f32 v173, v224, v225
	v_cvt_pk_bf16_f32 v174, v214, v215
	v_cvt_pk_bf16_f32 v175, v218, v219
	v_cvt_pk_bf16_f32 v176, v222, v223
	v_cvt_pk_bf16_f32 v177, v226, v227
	global_store_dwordx4 v169, v[170:173], s[22:23]
	global_store_dwordx4 v169, v[174:177], s[22:23] offset:64
	v_add_u32_e32 v245, 0x9000, v128
	global_load_dwordx4 v[212:215], v245, s[26:27]
	global_load_dwordx4 v[216:219], v245, s[26:27] offset:16
	global_load_dwordx4 v[220:223], v245, s[26:27] offset:32
	global_load_dwordx4 v[224:227], v245, s[26:27] offset:48
	v_add_f32_e32 v152, 0x42000000, v129
	v_mul_f32_e32 v152, s2, v152
	v_exp_f32_e32 v152, v152
	s_nop 0
	v_mul_f32_e32 v152, 0x3e000000, v152
	v_add_u32_e32 v168, 0x70000, v131
	s_waitcnt vmcnt(12)
	v_mov_b32_e32 v170, v228
	v_mov_b32_e32 v171, v230
	v_mov_b32_e32 v172, v229
	v_mov_b32_e32 v173, v231
	v_mov_b32_e32 v174, v232
	v_mov_b32_e32 v175, v234
	v_mov_b32_e32 v176, v233
	v_mov_b32_e32 v177, v235
	v_mov_b32_e32 v178, v236
	v_mov_b32_e32 v179, v238
	v_mov_b32_e32 v180, v237
	v_mov_b32_e32 v181, v239
	v_mov_b32_e32 v182, v240
	v_mov_b32_e32 v183, v242
	v_mov_b32_e32 v248, v241
	v_mov_b32_e32 v249, v243
	v_pk_mul_f32 v[228:229], v[84:85], v[172:173]
	v_pk_mul_f32 v[230:231], v[84:85], v[170:171]
	v_pk_mul_f32 v[232:233], v[86:87], v[176:177]
	v_pk_mul_f32 v[234:235], v[86:87], v[174:175]
	v_pk_mul_f32 v[236:237], v[80:81], v[180:181]
	v_pk_mul_f32 v[238:239], v[80:81], v[178:179]
	v_pk_mul_f32 v[240:241], v[82:83], v[248:249]
	v_pk_mul_f32 v[242:243], v[82:83], v[182:183]
	v_pk_fma_f32 v[228:229], v[92:93], v[170:171], v[228:229] neg_lo:[0,0,1] neg_hi:[0,0,1]
	v_pk_fma_f32 v[230:231], v[92:93], v[172:173], v[230:231]
	v_pk_fma_f32 v[232:233], v[94:95], v[174:175], v[232:233] neg_lo:[0,0,1] neg_hi:[0,0,1]
	v_pk_fma_f32 v[234:235], v[94:95], v[176:177], v[234:235]
	v_pk_fma_f32 v[236:237], v[88:89], v[178:179], v[236:237] neg_lo:[0,0,1] neg_hi:[0,0,1]
	v_pk_fma_f32 v[238:239], v[88:89], v[180:181], v[238:239]
	v_pk_fma_f32 v[240:241], v[90:91], v[182:183], v[240:241] neg_lo:[0,0,1] neg_hi:[0,0,1]
	v_pk_fma_f32 v[242:243], v[90:91], v[248:249], v[242:243]
	v_pk_mul_f32 v[228:229], v[152:153], v[228:229] op_sel_hi:[0,1]
	v_pk_mul_f32 v[230:231], v[152:153], v[230:231] op_sel_hi:[0,1]
	v_pk_mul_f32 v[232:233], v[152:153], v[232:233] op_sel_hi:[0,1]
	v_pk_mul_f32 v[234:235], v[152:153], v[234:235] op_sel_hi:[0,1]
	v_pk_mul_f32 v[236:237], v[152:153], v[236:237] op_sel_hi:[0,1]
	v_pk_mul_f32 v[238:239], v[152:153], v[238:239] op_sel_hi:[0,1]
	v_pk_mul_f32 v[240:241], v[152:153], v[240:241] op_sel_hi:[0,1]
	v_pk_mul_f32 v[242:243], v[152:153], v[242:243] op_sel_hi:[0,1]
	v_cvt_pk_bf16_f32 v170, v228, v229
	v_cvt_pk_bf16_f32 v171, v232, v233
	v_cvt_pk_bf16_f32 v172, v236, v237
	v_cvt_pk_bf16_f32 v173, v240, v241
	v_cvt_pk_bf16_f32 v174, v230, v231
	v_cvt_pk_bf16_f32 v175, v234, v235
	v_cvt_pk_bf16_f32 v176, v238, v239
	v_cvt_pk_bf16_f32 v177, v242, v243
	global_store_dwordx4 v168, v[170:173], s[22:23]
	global_store_dwordx4 v168, v[174:177], s[22:23] offset:64
	v_add_u32_e32 v246, 0xa000, v128
	global_load_dwordx4 v[228:231], v246, s[26:27]
	global_load_dwordx4 v[232:235], v246, s[26:27] offset:16
	global_load_dwordx4 v[236:239], v246, s[26:27] offset:32
	global_load_dwordx4 v[240:243], v246, s[26:27] offset:48
	v_add_f32_e32 v152, 0x42400000, v129
	v_mul_f32_e32 v152, s2, v152
	v_exp_f32_e32 v152, v152
	s_nop 0
	v_mul_f32_e32 v152, 0x3e000000, v152
	v_add_u32_e32 v169, 0xa8000, v131
	s_waitcnt vmcnt(12)
; __device__ __forceinline__ u32x4 pack8(const float (&v)[8]) { u32x4 w; w.x = cvtpk(v[0], v[1]); w.y = cvtpk(v[2], v[3]); w.z = cvtpk(v[4], v[5]); w.w = cvtpk(v[6], v[7]); return w; }
;     template <int TYPE> __device__ __forceinline__ void run(const Acc& acc, const Unit& u, int wr, int wc, int fr, int fq) const {
;     ...
;                 if (TYPE == 0 || TYPE == 1) {
;                     const int pos = row & (SEQ - 1);
;                     const f32x4* tp = (const f32x4*)(tab + ((size_t)pos * 32 + 8 * fq) * 2);
;                     const float lgp = lg2gamma(((u.pn & 1) << 2) + wc) * (float)pos;
;                     const float sc = (TYPE == 1) ? 0.125f * __builtin_amdgcn_exp2f(-lgp) : __builtin_amdgcn_exp2f(lgp);
; #pragma unroll
;                     for (int jj = 0; jj < 4; ++jj) { const f32x4 cs = tp[jj];
;                         { const float t1 = v[0][2 * jj], t2 = v[1][2 * jj]; v[0][2 * jj] = (t1 * cs.x - t2 * cs.y) * sc; v[1][2 * jj] = (t1 * cs.y + t2 * cs.x) * sc; }
;                         { const float t1 = v[0][2 * jj + 1], t2 = v[1][2 * jj + 1]; v[0][2 * jj + 1] = (t1 * cs.z - t2 * cs.w) * sc; v[1][2 * jj + 1] = (t1 * cs.w + t2 * cs.z) * sc; } }
;                 }
;                 if (TYPE == 3) {
; #pragma unroll
;                     for (int bj = 0; bj < 2; ++bj)
; #pragma unroll
;                         for (int j = 0; j < 8; ++j) { const float x = v[bj][j]; v[bj][j] = x * __builtin_amdgcn_rcpf(1.0f + __builtin_amdgcn_exp2f(-1.4426950408889634f * x)); }
;                 }
;                 if (TYPE == 4 || TYPE == 5) {
;                     float ss = 0.f;
; #pragma unroll
;                     for (int bj = 0; bj < 2; ++bj)
; #pragma unroll
;                         for (int j = 0; j < 8; ++j) ss += v[bj][j] * v[bj][j];
;                     ss = quad_sum(ss);
;                     const float r = rsqrtf(ss * (1.0f / 64.0f) + EPS);
; #pragma unroll
;                     for (int bj = 0; bj < 2; ++bj)
; #pragma unroll
;                         for (int j = 0; j < 8; ++j) v[bj][j] = v[bj][j] * r * g[bj][j];
;                 }
;                 bf16_t* rowp = Z + (size_t)row * DIN + colbase;
;                 *(u32x4*)(rowp) = pack8(v[0]); *(u32x4*)(rowp + 32) = pack8(v[1]);
	v_mov_b32_e32 v170, v186
	v_mov_b32_e32 v171, v188
	v_mov_b32_e32 v172, v187
	v_mov_b32_e32 v173, v189
	v_mov_b32_e32 v174, v190
	v_mov_b32_e32 v175, v192
	v_mov_b32_e32 v176, v191
	v_mov_b32_e32 v177, v193
	v_mov_b32_e32 v178, v194
	v_mov_b32_e32 v179, v196
	v_mov_b32_e32 v180, v195
	v_mov_b32_e32 v181, v197
	v_mov_b32_e32 v182, v198
	v_mov_b32_e32 v183, v200
	v_mov_b32_e32 v248, v199
	v_mov_b32_e32 v249, v201
	v_pk_mul_f32 v[186:187], v[68:69], v[172:173]
	v_pk_mul_f32 v[188:189], v[68:69], v[170:171]
	v_pk_mul_f32 v[190:191], v[70:71], v[176:177]
	v_pk_mul_f32 v[192:193], v[70:71], v[174:175]
	v_pk_mul_f32 v[194:195], v[64:65], v[180:181]
	v_pk_mul_f32 v[196:197], v[64:65], v[178:179]
	v_pk_mul_f32 v[198:199], v[66:67], v[248:249]
	v_pk_mul_f32 v[200:201], v[66:67], v[182:183]
	v_pk_fma_f32 v[186:187], v[76:77], v[170:171], v[186:187] neg_lo:[0,0,1] neg_hi:[0,0,1]
	v_pk_fma_f32 v[188:189], v[76:77], v[172:173], v[188:189]
	v_pk_fma_f32 v[190:191], v[78:79], v[174:175], v[190:191] neg_lo:[0,0,1] neg_hi:[0,0,1]
	v_pk_fma_f32 v[192:193], v[78:79], v[176:177], v[192:193]
	v_pk_fma_f32 v[194:195], v[72:73], v[178:179], v[194:195] neg_lo:[0,0,1] neg_hi:[0,0,1]
	v_pk_fma_f32 v[196:197], v[72:73], v[180:181], v[196:197]
	v_pk_fma_f32 v[198:199], v[74:75], v[182:183], v[198:199] neg_lo:[0,0,1] neg_hi:[0,0,1]
	v_pk_fma_f32 v[200:201], v[74:75], v[248:249], v[200:201]
	v_pk_mul_f32 v[186:187], v[152:153], v[186:187] op_sel_hi:[0,1]
	v_pk_mul_f32 v[188:189], v[152:153], v[188:189] op_sel_hi:[0,1]
	v_pk_mul_f32 v[190:191], v[152:153], v[190:191] op_sel_hi:[0,1]
	v_pk_mul_f32 v[192:193], v[152:153], v[192:193] op_sel_hi:[0,1]
	v_pk_mul_f32 v[194:195], v[152:153], v[194:195] op_sel_hi:[0,1]
	v_pk_mul_f32 v[196:197], v[152:153], v[196:197] op_sel_hi:[0,1]
	v_pk_mul_f32 v[198:199], v[152:153], v[198:199] op_sel_hi:[0,1]
	v_pk_mul_f32 v[200:201], v[152:153], v[200:201] op_sel_hi:[0,1]
	v_cvt_pk_bf16_f32 v170, v186, v187
	v_cvt_pk_bf16_f32 v171, v190, v191
	v_cvt_pk_bf16_f32 v172, v194, v195
	v_cvt_pk_bf16_f32 v173, v198, v199
	v_cvt_pk_bf16_f32 v174, v188, v189
	v_cvt_pk_bf16_f32 v175, v192, v193
	v_cvt_pk_bf16_f32 v176, v196, v197
	v_cvt_pk_bf16_f32 v177, v200, v201
	global_store_dwordx4 v169, v[170:173], s[22:23]
	global_store_dwordx4 v169, v[174:177], s[22:23] offset:64
	v_add_u32_e32 v247, 0xb000, v128
	global_load_dwordx4 v[186:189], v247, s[26:27]
	global_load_dwordx4 v[190:193], v247, s[26:27] offset:16
	global_load_dwordx4 v[194:197], v247, s[26:27] offset:32
	global_load_dwordx4 v[198:201], v247, s[26:27] offset:48
	v_add_f32_e32 v152, 0x43000000, v129
	v_mul_f32_e32 v152, s2, v152
	v_exp_f32_e32 v152, v152
	s_nop 0
	v_mul_f32_e32 v152, 0x3e000000, v152
	v_add_u32_e32 v168, 0x1c0000, v131
	s_waitcnt vmcnt(12)
	v_mov_b32_e32 v170, v132
	v_mov_b32_e32 v171, v134
	v_mov_b32_e32 v172, v133
	v_mov_b32_e32 v173, v135
	v_mov_b32_e32 v174, v136
	v_mov_b32_e32 v175, v138
	v_mov_b32_e32 v176, v137
	v_mov_b32_e32 v177, v139
	v_mov_b32_e32 v178, v140
	v_mov_b32_e32 v179, v142
	v_mov_b32_e32 v180, v141
	v_mov_b32_e32 v181, v143
	v_mov_b32_e32 v182, v164
	v_mov_b32_e32 v183, v166
	v_mov_b32_e32 v248, v165
	v_mov_b32_e32 v249, v167
	v_pk_mul_f32 v[132:133], v[52:53], v[172:173]
	v_pk_mul_f32 v[134:135], v[52:53], v[170:171]
	v_pk_mul_f32 v[136:137], v[54:55], v[176:177]
	v_pk_mul_f32 v[138:139], v[54:55], v[174:175]
	v_pk_mul_f32 v[140:141], v[48:49], v[180:181]
	v_pk_mul_f32 v[142:143], v[48:49], v[178:179]
	v_pk_mul_f32 v[164:165], v[50:51], v[248:249]
	v_pk_mul_f32 v[166:167], v[50:51], v[182:183]
	v_pk_fma_f32 v[132:133], v[60:61], v[170:171], v[132:133] neg_lo:[0,0,1] neg_hi:[0,0,1]
	v_pk_fma_f32 v[134:135], v[60:61], v[172:173], v[134:135]
	v_pk_fma_f32 v[136:137], v[62:63], v[174:175], v[136:137] neg_lo:[0,0,1] neg_hi:[0,0,1]
	v_pk_fma_f32 v[138:139], v[62:63], v[176:177], v[138:139]
	v_pk_fma_f32 v[140:141], v[56:57], v[178:179], v[140:141] neg_lo:[0,0,1] neg_hi:[0,0,1]
	v_pk_fma_f32 v[142:143], v[56:57], v[180:181], v[142:143]
	v_pk_fma_f32 v[164:165], v[58:59], v[182:183], v[164:165] neg_lo:[0,0,1] neg_hi:[0,0,1]
	v_pk_fma_f32 v[166:167], v[58:59], v[248:249], v[166:167]
	v_pk_mul_f32 v[132:133], v[152:153], v[132:133] op_sel_hi:[0,1]
	v_pk_mul_f32 v[134:135], v[152:153], v[134:135] op_sel_hi:[0,1]
	v_pk_mul_f32 v[136:137], v[152:153], v[136:137] op_sel_hi:[0,1]
	v_pk_mul_f32 v[138:139], v[152:153], v[138:139] op_sel_hi:[0,1]
	v_pk_mul_f32 v[140:141], v[152:153], v[140:141] op_sel_hi:[0,1]
	v_pk_mul_f32 v[142:143], v[152:153], v[142:143] op_sel_hi:[0,1]
	v_pk_mul_f32 v[164:165], v[152:153], v[164:165] op_sel_hi:[0,1]
	v_pk_mul_f32 v[166:167], v[152:153], v[166:167] op_sel_hi:[0,1]
	v_cvt_pk_bf16_f32 v170, v132, v133
	v_cvt_pk_bf16_f32 v171, v136, v137
	v_cvt_pk_bf16_f32 v172, v140, v141
	v_cvt_pk_bf16_f32 v173, v164, v165
	v_cvt_pk_bf16_f32 v174, v134, v135
	v_cvt_pk_bf16_f32 v175, v138, v139
	v_cvt_pk_bf16_f32 v176, v142, v143
	v_cvt_pk_bf16_f32 v177, v166, v167
	global_store_dwordx4 v168, v[170:173], s[22:23]
	global_store_dwordx4 v168, v[174:177], s[22:23] offset:64
	v_add_f32_e32 v152, 0x43100000, v129
	v_mul_f32_e32 v152, s2, v152
	v_exp_f32_e32 v152, v152
	s_nop 0
	v_mul_f32_e32 v152, 0x3e000000, v152
	v_add_u32_e32 v169, 0x1f8000, v131
	s_waitcnt vmcnt(8)
; __device__ __forceinline__ u32x4 pack8(const float (&v)[8]) { u32x4 w; w.x = cvtpk(v[0], v[1]); w.y = cvtpk(v[2], v[3]); w.z = cvtpk(v[4], v[5]); w.w = cvtpk(v[6], v[7]); return w; }
;     template <int TYPE> __device__ __forceinline__ void run(const Acc& acc, const Unit& u, int wr, int wc, int fr, int fq) const {
;     ...
;                 if (TYPE == 0 || TYPE == 1) {
;                     const int pos = row & (SEQ - 1);
;                     const f32x4* tp = (const f32x4*)(tab + ((size_t)pos * 32 + 8 * fq) * 2);
;                     const float lgp = lg2gamma(((u.pn & 1) << 2) + wc) * (float)pos;
;                     const float sc = (TYPE == 1) ? 0.125f * __builtin_amdgcn_exp2f(-lgp) : __builtin_amdgcn_exp2f(lgp);
; #pragma unroll
;                     for (int jj = 0; jj < 4; ++jj) { const f32x4 cs = tp[jj];
;                         { const float t1 = v[0][2 * jj], t2 = v[1][2 * jj]; v[0][2 * jj] = (t1 * cs.x - t2 * cs.y) * sc; v[1][2 * jj] = (t1 * cs.y + t2 * cs.x) * sc; }
;                         { const float t1 = v[0][2 * jj + 1], t2 = v[1][2 * jj + 1]; v[0][2 * jj + 1] = (t1 * cs.z - t2 * cs.w) * sc; v[1][2 * jj + 1] = (t1 * cs.w + t2 * cs.z) * sc; } }
;                 }
;                 if (TYPE == 3) {
; #pragma unroll
;                     for (int bj = 0; bj < 2; ++bj)
; #pragma unroll
;                         for (int j = 0; j < 8; ++j) { const float x = v[bj][j]; v[bj][j] = x * __builtin_amdgcn_rcpf(1.0f + __builtin_amdgcn_exp2f(-1.4426950408889634f * x)); }
;                 }
;                 if (TYPE == 4 || TYPE == 5) {
;                     float ss = 0.f;
; #pragma unroll
;                     for (int bj = 0; bj < 2; ++bj)
; #pragma unroll
;                         for (int j = 0; j < 8; ++j) ss += v[bj][j] * v[bj][j];
;                     ss = quad_sum(ss);
;                     const float r = rsqrtf(ss * (1.0f / 64.0f) + EPS);
; #pragma unroll
;                     for (int bj = 0; bj < 2; ++bj)
; #pragma unroll
;                         for (int j = 0; j < 8; ++j) v[bj][j] = v[bj][j] * r * g[bj][j];
;                 }
;                 bf16_t* rowp = Z + (size_t)row * DIN + colbase;
;                 *(u32x4*)(rowp) = pack8(v[0]); *(u32x4*)(rowp + 32) = pack8(v[1]);
	v_mov_b32_e32 v170, v212
	v_mov_b32_e32 v171, v214
	v_mov_b32_e32 v172, v213
	v_mov_b32_e32 v173, v215
	v_mov_b32_e32 v174, v216
	v_mov_b32_e32 v175, v218
	v_mov_b32_e32 v176, v217
	v_mov_b32_e32 v177, v219
	v_mov_b32_e32 v178, v220
	v_mov_b32_e32 v179, v222
	v_mov_b32_e32 v180, v221
	v_mov_b32_e32 v181, v223
	v_mov_b32_e32 v182, v224
	v_mov_b32_e32 v183, v226
	v_mov_b32_e32 v248, v225
	v_mov_b32_e32 v249, v227
	v_pk_mul_f32 v[212:213], v[36:37], v[172:173]
	v_pk_mul_f32 v[214:215], v[36:37], v[170:171]
	v_pk_mul_f32 v[216:217], v[38:39], v[176:177]
	v_pk_mul_f32 v[218:219], v[38:39], v[174:175]
	v_pk_mul_f32 v[220:221], v[32:33], v[180:181]
	v_pk_mul_f32 v[222:223], v[32:33], v[178:179]
	v_pk_mul_f32 v[224:225], v[34:35], v[248:249]
	v_pk_mul_f32 v[226:227], v[34:35], v[182:183]
	v_pk_fma_f32 v[212:213], v[44:45], v[170:171], v[212:213] neg_lo:[0,0,1] neg_hi:[0,0,1]
	v_pk_fma_f32 v[214:215], v[44:45], v[172:173], v[214:215]
	v_pk_fma_f32 v[216:217], v[46:47], v[174:175], v[216:217] neg_lo:[0,0,1] neg_hi:[0,0,1]
	v_pk_fma_f32 v[218:219], v[46:47], v[176:177], v[218:219]
	v_pk_fma_f32 v[220:221], v[40:41], v[178:179], v[220:221] neg_lo:[0,0,1] neg_hi:[0,0,1]
	v_pk_fma_f32 v[222:223], v[40:41], v[180:181], v[222:223]
	v_pk_fma_f32 v[224:225], v[42:43], v[182:183], v[224:225] neg_lo:[0,0,1] neg_hi:[0,0,1]
	v_pk_fma_f32 v[226:227], v[42:43], v[248:249], v[226:227]
	v_pk_mul_f32 v[212:213], v[152:153], v[212:213] op_sel_hi:[0,1]
	v_pk_mul_f32 v[214:215], v[152:153], v[214:215] op_sel_hi:[0,1]
	v_pk_mul_f32 v[216:217], v[152:153], v[216:217] op_sel_hi:[0,1]
	v_pk_mul_f32 v[218:219], v[152:153], v[218:219] op_sel_hi:[0,1]
	v_pk_mul_f32 v[220:221], v[152:153], v[220:221] op_sel_hi:[0,1]
	v_pk_mul_f32 v[222:223], v[152:153], v[222:223] op_sel_hi:[0,1]
	v_pk_mul_f32 v[224:225], v[152:153], v[224:225] op_sel_hi:[0,1]
	v_pk_mul_f32 v[226:227], v[152:153], v[226:227] op_sel_hi:[0,1]
	v_cvt_pk_bf16_f32 v170, v212, v213
	v_cvt_pk_bf16_f32 v171, v216, v217
	v_cvt_pk_bf16_f32 v172, v220, v221
	v_cvt_pk_bf16_f32 v173, v224, v225
	v_cvt_pk_bf16_f32 v174, v214, v215
	v_cvt_pk_bf16_f32 v175, v218, v219
	v_cvt_pk_bf16_f32 v176, v222, v223
	v_cvt_pk_bf16_f32 v177, v226, v227
	global_store_dwordx4 v169, v[170:173], s[22:23]
	global_store_dwordx4 v169, v[174:177], s[22:23] offset:64
	v_add_f32_e32 v152, 0x43200000, v129
	v_mul_f32_e32 v152, s2, v152
	v_exp_f32_e32 v152, v152
	s_nop 0
	v_mul_f32_e32 v152, 0x3e000000, v152
	v_add_u32_e32 v168, 0x230000, v131
	s_waitcnt vmcnt(4)
; __device__ __forceinline__ u32x4 pack8(const float (&v)[8]) { u32x4 w; w.x = cvtpk(v[0], v[1]); w.y = cvtpk(v[2], v[3]); w.z = cvtpk(v[4], v[5]); w.w = cvtpk(v[6], v[7]); return w; }
;     template <int TYPE> __device__ __forceinline__ void run(const Acc& acc, const Unit& u, int wr, int wc, int fr, int fq) const {
;     ...
;                 if (TYPE == 0 || TYPE == 1) {
;                     const int pos = row & (SEQ - 1);
;                     const f32x4* tp = (const f32x4*)(tab + ((size_t)pos * 32 + 8 * fq) * 2);
;                     const float lgp = lg2gamma(((u.pn & 1) << 2) + wc) * (float)pos;
;                     const float sc = (TYPE == 1) ? 0.125f * __builtin_amdgcn_exp2f(-lgp) : __builtin_amdgcn_exp2f(lgp);
; #pragma unroll
;                     for (int jj = 0; jj < 4; ++jj) { const f32x4 cs = tp[jj];
;                         { const float t1 = v[0][2 * jj], t2 = v[1][2 * jj]; v[0][2 * jj] = (t1 * cs.x - t2 * cs.y) * sc; v[1][2 * jj] = (t1 * cs.y + t2 * cs.x) * sc; }
;                         { const float t1 = v[0][2 * jj + 1], t2 = v[1][2 * jj + 1]; v[0][2 * jj + 1] = (t1 * cs.z - t2 * cs.w) * sc; v[1][2 * jj + 1] = (t1 * cs.w + t2 * cs.z) * sc; } }
;                 }
;                 if (TYPE == 3) {
; #pragma unroll
;                     for (int bj = 0; bj < 2; ++bj)
; #pragma unroll
;                         for (int j = 0; j < 8; ++j) { const float x = v[bj][j]; v[bj][j] = x * __builtin_amdgcn_rcpf(1.0f + __builtin_amdgcn_exp2f(-1.4426950408889634f * x)); }
;                 }
;                 if (TYPE == 4 || TYPE == 5) {
;                     float ss = 0.f;
; #pragma unroll
;                     for (int bj = 0; bj < 2; ++bj)
; #pragma unroll
;                         for (int j = 0; j < 8; ++j) ss += v[bj][j] * v[bj][j];
;                     ss = quad_sum(ss);
;                     const float r = rsqrtf(ss * (1.0f / 64.0f) + EPS);
; #pragma unroll
;                     for (int bj = 0; bj < 2; ++bj)
; #pragma unroll
;                         for (int j = 0; j < 8; ++j) v[bj][j] = v[bj][j] * r * g[bj][j];
;                 }
;                 bf16_t* rowp = Z + (size_t)row * DIN + colbase;
;                 *(u32x4*)(rowp) = pack8(v[0]); *(u32x4*)(rowp + 32) = pack8(v[1]);
	v_mov_b32_e32 v170, v228
	v_mov_b32_e32 v171, v230
	v_mov_b32_e32 v172, v229
	v_mov_b32_e32 v173, v231
	v_mov_b32_e32 v174, v232
	v_mov_b32_e32 v175, v234
	v_mov_b32_e32 v176, v233
	v_mov_b32_e32 v177, v235
	v_mov_b32_e32 v178, v236
	v_mov_b32_e32 v179, v238
	v_mov_b32_e32 v180, v237
	v_mov_b32_e32 v181, v239
	v_mov_b32_e32 v182, v240
	v_mov_b32_e32 v183, v242
	v_mov_b32_e32 v248, v241
	v_mov_b32_e32 v249, v243
	v_pk_mul_f32 v[228:229], v[20:21], v[172:173]
	v_pk_mul_f32 v[230:231], v[20:21], v[170:171]
	v_pk_mul_f32 v[232:233], v[22:23], v[176:177]
	v_pk_mul_f32 v[234:235], v[22:23], v[174:175]
	v_pk_mul_f32 v[236:237], v[16:17], v[180:181]
	v_pk_mul_f32 v[238:239], v[16:17], v[178:179]
	v_pk_mul_f32 v[240:241], v[18:19], v[248:249]
	v_pk_mul_f32 v[242:243], v[18:19], v[182:183]
	v_pk_fma_f32 v[228:229], v[28:29], v[170:171], v[228:229] neg_lo:[0,0,1] neg_hi:[0,0,1]
	v_pk_fma_f32 v[230:231], v[28:29], v[172:173], v[230:231]
	v_pk_fma_f32 v[232:233], v[30:31], v[174:175], v[232:233] neg_lo:[0,0,1] neg_hi:[0,0,1]
	v_pk_fma_f32 v[234:235], v[30:31], v[176:177], v[234:235]
	v_pk_fma_f32 v[236:237], v[24:25], v[178:179], v[236:237] neg_lo:[0,0,1] neg_hi:[0,0,1]
	v_pk_fma_f32 v[238:239], v[24:25], v[180:181], v[238:239]
	v_pk_fma_f32 v[240:241], v[26:27], v[182:183], v[240:241] neg_lo:[0,0,1] neg_hi:[0,0,1]
	v_pk_fma_f32 v[242:243], v[26:27], v[248:249], v[242:243]
	v_pk_mul_f32 v[228:229], v[152:153], v[228:229] op_sel_hi:[0,1]
	v_pk_mul_f32 v[230:231], v[152:153], v[230:231] op_sel_hi:[0,1]
	v_pk_mul_f32 v[232:233], v[152:153], v[232:233] op_sel_hi:[0,1]
	v_pk_mul_f32 v[234:235], v[152:153], v[234:235] op_sel_hi:[0,1]
	v_pk_mul_f32 v[236:237], v[152:153], v[236:237] op_sel_hi:[0,1]
	v_pk_mul_f32 v[238:239], v[152:153], v[238:239] op_sel_hi:[0,1]
	v_pk_mul_f32 v[240:241], v[152:153], v[240:241] op_sel_hi:[0,1]
	v_pk_mul_f32 v[242:243], v[152:153], v[242:243] op_sel_hi:[0,1]
	v_cvt_pk_bf16_f32 v170, v228, v229
	v_cvt_pk_bf16_f32 v171, v232, v233
	v_cvt_pk_bf16_f32 v172, v236, v237
	v_cvt_pk_bf16_f32 v173, v240, v241
	v_cvt_pk_bf16_f32 v174, v230, v231
	v_cvt_pk_bf16_f32 v175, v234, v235
	v_cvt_pk_bf16_f32 v176, v238, v239
	v_cvt_pk_bf16_f32 v177, v242, v243
	global_store_dwordx4 v168, v[170:173], s[22:23]
	global_store_dwordx4 v168, v[174:177], s[22:23] offset:64
	v_add_f32_e32 v152, 0x43300000, v129
	v_mul_f32_e32 v152, s2, v152
	v_exp_f32_e32 v152, v152
	s_nop 0
	v_mul_f32_e32 v152, 0x3e000000, v152
	v_add_u32_e32 v169, 0x268000, v131
	s_waitcnt vmcnt(0)
	v_mov_b32_e32 v170, v186
	v_mov_b32_e32 v171, v188
	v_mov_b32_e32 v172, v187
	v_mov_b32_e32 v173, v189
	v_mov_b32_e32 v174, v190
	v_mov_b32_e32 v175, v192
	v_mov_b32_e32 v176, v191
	v_mov_b32_e32 v177, v193
	v_mov_b32_e32 v178, v194
	v_mov_b32_e32 v179, v196
	v_mov_b32_e32 v180, v195
	v_mov_b32_e32 v181, v197
	v_mov_b32_e32 v182, v198
	v_mov_b32_e32 v183, v200
	v_mov_b32_e32 v248, v199
	v_mov_b32_e32 v249, v201
	v_pk_mul_f32 v[186:187], v[4:5], v[172:173]
	v_pk_mul_f32 v[188:189], v[4:5], v[170:171]
	v_pk_mul_f32 v[190:191], v[6:7], v[176:177]
	v_pk_mul_f32 v[192:193], v[6:7], v[174:175]
	v_pk_mul_f32 v[194:195], v[0:1], v[180:181]
	v_pk_mul_f32 v[196:197], v[0:1], v[178:179]
	v_pk_mul_f32 v[198:199], v[2:3], v[248:249]
	v_pk_mul_f32 v[200:201], v[2:3], v[182:183]
	v_pk_fma_f32 v[186:187], v[12:13], v[170:171], v[186:187] neg_lo:[0,0,1] neg_hi:[0,0,1]
	v_pk_fma_f32 v[188:189], v[12:13], v[172:173], v[188:189]
	v_pk_fma_f32 v[190:191], v[14:15], v[174:175], v[190:191] neg_lo:[0,0,1] neg_hi:[0,0,1]
	v_pk_fma_f32 v[192:193], v[14:15], v[176:177], v[192:193]
	v_pk_fma_f32 v[194:195], v[8:9], v[178:179], v[194:195] neg_lo:[0,0,1] neg_hi:[0,0,1]
	v_pk_fma_f32 v[196:197], v[8:9], v[180:181], v[196:197]
	v_pk_fma_f32 v[198:199], v[10:11], v[182:183], v[198:199] neg_lo:[0,0,1] neg_hi:[0,0,1]
	v_pk_fma_f32 v[200:201], v[10:11], v[248:249], v[200:201]
	v_pk_mul_f32 v[186:187], v[152:153], v[186:187] op_sel_hi:[0,1]
	v_pk_mul_f32 v[188:189], v[152:153], v[188:189] op_sel_hi:[0,1]
	v_pk_mul_f32 v[190:191], v[152:153], v[190:191] op_sel_hi:[0,1]
	v_pk_mul_f32 v[192:193], v[152:153], v[192:193] op_sel_hi:[0,1]
	v_pk_mul_f32 v[194:195], v[152:153], v[194:195] op_sel_hi:[0,1]
	v_pk_mul_f32 v[196:197], v[152:153], v[196:197] op_sel_hi:[0,1]
	v_pk_mul_f32 v[198:199], v[152:153], v[198:199] op_sel_hi:[0,1]
	v_pk_mul_f32 v[200:201], v[152:153], v[200:201] op_sel_hi:[0,1]
	v_cvt_pk_bf16_f32 v170, v186, v187
	v_cvt_pk_bf16_f32 v171, v190, v191
	v_cvt_pk_bf16_f32 v172, v194, v195
	v_cvt_pk_bf16_f32 v173, v198, v199
	v_cvt_pk_bf16_f32 v174, v188, v189
	v_cvt_pk_bf16_f32 v175, v192, v193
	v_cvt_pk_bf16_f32 v176, v196, v197
	v_cvt_pk_bf16_f32 v177, v200, v201
	global_store_dwordx4 v169, v[170:173], s[22:23]
	global_store_dwordx4 v169, v[174:177], s[22:23] offset:64
	s_andn2_b64 vcc, exec, s[4:5]
	s_mov_b64 s[2:3], -1
	s_branch .Lz_epi_done

;     template <int TYPE> __device__ __forceinline__ void run(const Acc& acc, const Unit& u, int wr, int wc, int fr, int fq) const {
;     ...
;         for (int ai = 0; ai < 2; ++ai)
; #pragma unroll
;             for (int m = 0; m < 4; ++m) {
;                 const int row = u.pm * 256 + ai * 128 + wr * 64 + m * 16 + fr;
;                 float v[2][8];
; #pragma unroll
;                 for (int bj = 0; bj < 2; ++bj)
; #pragma unroll
;                     for (int n = 0; n < 2; ++n)
; #pragma unroll
;                         for (int i = 0; i < 4; ++i) v[bj][4 * n + i] = acc[ai][bj][m][n][i];
;                 if (TYPE == 0 || TYPE == 1) {
;                     const int pos = row & (SEQ - 1);
;                     const f32x4* tp = (const f32x4*)(tab + ((size_t)pos * 32 + 8 * fq) * 2);
;                     const float lgp = lg2gamma(((u.pn & 1) << 2) + wc) * (float)pos;
;                     const float sc = (TYPE == 1) ? 0.125f * __builtin_amdgcn_exp2f(-lgp) : __builtin_amdgcn_exp2f(lgp);
; #pragma unroll
;                     for (int jj = 0; jj < 4; ++jj) { const f32x4 cs = tp[jj];
;                         { const float t1 = v[0][2 * jj], t2 = v[1][2 * jj]; v[0][2 * jj] = (t1 * cs.x - t2 * cs.y) * sc; v[1][2 * jj] = (t1 * cs.y + t2 * cs.x) * sc; }
;                         { const float t1 = v[0][2 * jj + 1], t2 = v[1][2 * jj + 1]; v[0][2 * jj + 1] = (t1 * cs.z - t2 * cs.w) * sc; v[1][2 * jj + 1] = (t1 * cs.w + t2 * cs.z) * sc; } }
;                 }
;                 if (TYPE == 3) {
; #pragma unroll
;                     for (int bj = 0; bj < 2; ++bj)
; #pragma unroll
;                         for (int j = 0; j < 8; ++j) { const float x = v[bj][j]; v[bj][j] = x * __builtin_amdgcn_rcpf(1.0f + __builtin_amdgcn_exp2f(-1.4426950408889634f * x)); }
;                 }
;                 if (TYPE == 4 || TYPE == 5) {
;                     float ss = 0.f;
; #pragma unroll
;                     for (int bj = 0; bj < 2; ++bj)
; #pragma unroll
;                         for (int j = 0; j < 8; ++j) ss += v[bj][j] * v[bj][j];
;                     ss = quad_sum(ss);
;                     const float r = rsqrtf(ss * (1.0f / 64.0f) + EPS);
; #pragma unroll
;                     for (int bj = 0; bj < 2; ++bj)
; #pragma unroll
;                         for (int j = 0; j < 8; ++j) v[bj][j] = v[bj][j] * r * g[bj][j];
;                 }
.LBB0_302:
	s_andn2_b64 vcc, exec, s[2:3]
	s_cbranch_vccnz .LBB0_472
	s_lshl_b32 s2, s44, 2
	s_and_b32 s2, s2, 4
	s_or_b32 s6, s2, s31
	s_mov_b32 s2, 0xbd3b9ca6
	s_cmp_eq_u32 s6, 1
	s_cselect_b32 s2, 0xbcba1f74, s2
	s_cmp_eq_u32 s6, 2
	s_cselect_b32 s2, 0xbc3963dd, s2
	s_cmp_eq_u32 s6, 3
	s_cselect_b32 s2, 0xbbb906ce, s2
	s_cmp_eq_u32 s6, 4
	s_cselect_b32 s2, 0xbb38d875, s2
	s_cmp_eq_u32 s6, 5
	s_cselect_b32 s2, 0xbab8c154, s2
	s_cmp_eq_u32 s6, 6
	s_cselect_b32 s2, 0xba38b5c7, s2
	s_cmp_eq_u32 s6, 7
	s_cselect_b32 s2, 0xb9b8b001, s2
	s_lshl_b32 s3, s46, 8
	s_add_i32 s3, s3, s79
	v_add_u32_e32 v130, s3, v209
	v_and_b32_e32 v159, 0x7ff, v130
	v_lshlrev_b32_e32 v128, 8, v159
	v_lshl_add_u32 v128, v210, 6, v128
	v_mov_b32_e32 v244, v128
	global_load_dwordx4 v[132:135], v244, s[26:27]
	global_load_dwordx4 v[136:139], v244, s[26:27] offset:16
	global_load_dwordx4 v[140:143], v244, s[26:27] offset:32
	global_load_dwordx4 v[164:167], v244, s[26:27] offset:48
	v_add_u32_e32 v245, 0x1000, v128
	global_load_dwordx4 v[212:215], v245, s[26:27]
	global_load_dwordx4 v[216:219], v245, s[26:27] offset:16
	global_load_dwordx4 v[220:223], v245, s[26:27] offset:32
	global_load_dwordx4 v[224:227], v245, s[26:27] offset:48
	v_add_u32_e32 v246, 0x2000, v128
	global_load_dwordx4 v[228:231], v246, s[26:27]
	global_load_dwordx4 v[232:235], v246, s[26:27] offset:16
	global_load_dwordx4 v[236:239], v246, s[26:27] offset:32
	global_load_dwordx4 v[240:243], v246, s[26:27] offset:48
	v_add_u32_e32 v247, 0x3000, v128
	global_load_dwordx4 v[186:189], v247, s[26:27]
	global_load_dwordx4 v[190:193], v247, s[26:27] offset:16
	global_load_dwordx4 v[194:197], v247, s[26:27] offset:32
	global_load_dwordx4 v[198:201], v247, s[26:27] offset:48
	v_cvt_f32_u32_e32 v129, v159
	s_lshl_b32 s3, s44, 8
	s_or_b32 s3, s3, s86
	v_lshl_add_u32 v162, v210, 3, s3
	v_mul_u32_u24_e32 v131, 0x3800, v130
	v_lshl_add_u32 v131, v162, 1, v131
	v_mov_b32_e32 v152, v129
	v_mul_f32_e32 v152, s2, v152
	v_exp_f32_e32 v152, v152
	v_mov_b32_e32 v168, v131
	s_waitcnt vmcnt(12)
	v_mov_b32_e32 v170, v132
	v_mov_b32_e32 v171, v134
	v_mov_b32_e32 v172, v133
	v_mov_b32_e32 v173, v135
	v_mov_b32_e32 v174, v136
	v_mov_b32_e32 v175, v138
	v_mov_b32_e32 v176, v137
	v_mov_b32_e32 v177, v139
	v_mov_b32_e32 v178, v140
	v_mov_b32_e32 v179, v142
	v_mov_b32_e32 v180, v141
	v_mov_b32_e32 v181, v143
	v_mov_b32_e32 v182, v164
	v_mov_b32_e32 v183, v166
	v_mov_b32_e32 v248, v165
	v_mov_b32_e32 v249, v167
	v_pk_mul_f32 v[132:133], v[116:117], v[172:173]
	v_pk_mul_f32 v[134:135], v[116:117], v[170:171]
	v_pk_mul_f32 v[136:137], v[118:119], v[176:177]
	v_pk_mul_f32 v[138:139], v[118:119], v[174:175]
	v_pk_mul_f32 v[140:141], v[112:113], v[180:181]
	v_pk_mul_f32 v[142:143], v[112:113], v[178:179]
	v_pk_mul_f32 v[164:165], v[114:115], v[248:249]
	v_pk_mul_f32 v[166:167], v[114:115], v[182:183]
	v_pk_fma_f32 v[132:133], v[124:125], v[170:171], v[132:133] neg_lo:[0,0,1] neg_hi:[0,0,1]
	v_pk_fma_f32 v[134:135], v[124:125], v[172:173], v[134:135]
	v_pk_fma_f32 v[136:137], v[126:127], v[174:175], v[136:137] neg_lo:[0,0,1] neg_hi:[0,0,1]
	v_pk_fma_f32 v[138:139], v[126:127], v[176:177], v[138:139]
	v_pk_fma_f32 v[140:141], v[120:121], v[178:179], v[140:141] neg_lo:[0,0,1] neg_hi:[0,0,1]
	v_pk_fma_f32 v[142:143], v[120:121], v[180:181], v[142:143]
	v_pk_fma_f32 v[164:165], v[122:123], v[182:183], v[164:165] neg_lo:[0,0,1] neg_hi:[0,0,1]
	v_pk_fma_f32 v[166:167], v[122:123], v[248:249], v[166:167]
	v_pk_mul_f32 v[132:133], v[152:153], v[132:133] op_sel_hi:[0,1]
	v_pk_mul_f32 v[134:135], v[152:153], v[134:135] op_sel_hi:[0,1]
	v_pk_mul_f32 v[136:137], v[152:153], v[136:137] op_sel_hi:[0,1]
	v_pk_mul_f32 v[138:139], v[152:153], v[138:139] op_sel_hi:[0,1]
	v_pk_mul_f32 v[140:141], v[152:153], v[140:141] op_sel_hi:[0,1]
	v_pk_mul_f32 v[142:143], v[152:153], v[142:143] op_sel_hi:[0,1]
	v_pk_mul_f32 v[164:165], v[152:153], v[164:165] op_sel_hi:[0,1]
	v_pk_mul_f32 v[166:167], v[152:153], v[166:167] op_sel_hi:[0,1]
	v_cvt_pk_bf16_f32 v170, v132, v133
	v_cvt_pk_bf16_f32 v171, v136, v137
	v_cvt_pk_bf16_f32 v172, v140, v141
	v_cvt_pk_bf16_f32 v173, v164, v165
	v_cvt_pk_bf16_f32 v174, v134, v135
	v_cvt_pk_bf16_f32 v175, v138, v139
	v_cvt_pk_bf16_f32 v176, v142, v143
	v_cvt_pk_bf16_f32 v177, v166, v167
	global_store_dwordx4 v168, v[170:173], s[22:23]
	global_store_dwordx4 v168, v[174:177], s[22:23] offset:64
	v_add_u32_e32 v244, 0x8000, v128
	global_load_dwordx4 v[132:135], v244, s[26:27]
	global_load_dwordx4 v[136:139], v244, s[26:27] offset:16
	global_load_dwordx4 v[140:143], v244, s[26:27] offset:32
	global_load_dwordx4 v[164:167], v244, s[26:27] offset:48
	v_add_f32_e32 v152, 0x41800000, v129
	v_mul_f32_e32 v152, s2, v152
	v_exp_f32_e32 v152, v152
	v_add_u32_e32 v169, 0x38000, v131
	s_waitcnt vmcnt(12)
; __device__ __forceinline__ u32x4 pack8(const float (&v)[8]) { u32x4 w; w.x = cvtpk(v[0], v[1]); w.y = cvtpk(v[2], v[3]); w.z = cvtpk(v[4], v[5]); w.w = cvtpk(v[6], v[7]); return w; }
;     template <int TYPE> __device__ __forceinline__ void run(const Acc& acc, const Unit& u, int wr, int wc, int fr, int fq) const {
;     ...
;                 if (TYPE == 0 || TYPE == 1) {
;                     const int pos = row & (SEQ - 1);
;                     const f32x4* tp = (const f32x4*)(tab + ((size_t)pos * 32 + 8 * fq) * 2);
;                     const float lgp = lg2gamma(((u.pn & 1) << 2) + wc) * (float)pos;
;                     const float sc = (TYPE == 1) ? 0.125f * __builtin_amdgcn_exp2f(-lgp) : __builtin_amdgcn_exp2f(lgp);
; #pragma unroll
;                     for (int jj = 0; jj < 4; ++jj) { const f32x4 cs = tp[jj];
;                         { const float t1 = v[0][2 * jj], t2 = v[1][2 * jj]; v[0][2 * jj] = (t1 * cs.x - t2 * cs.y) * sc; v[1][2 * jj] = (t1 * cs.y + t2 * cs.x) * sc; }
;                         { const float t1 = v[0][2 * jj + 1], t2 = v[1][2 * jj + 1]; v[0][2 * jj + 1] = (t1 * cs.z - t2 * cs.w) * sc; v[1][2 * jj + 1] = (t1 * cs.w + t2 * cs.z) * sc; } }
;                 }
;     ...
;                 bf16_t* rowp = Z + (size_t)row * DIN + colbase;
;                 *(u32x4*)(rowp) = pack8(v[0]); *(u32x4*)(rowp + 32) = pack8(v[1]);
	v_mov_b32_e32 v170, v212
	v_mov_b32_e32 v171, v214
	v_mov_b32_e32 v172, v213
	v_mov_b32_e32 v173, v215
	v_mov_b32_e32 v174, v216
	v_mov_b32_e32 v175, v218
	v_mov_b32_e32 v176, v217
	v_mov_b32_e32 v177, v219
	v_mov_b32_e32 v178, v220
	v_mov_b32_e32 v179, v222
	v_mov_b32_e32 v180, v221
	v_mov_b32_e32 v181, v223
	v_mov_b32_e32 v182, v224
	v_mov_b32_e32 v183, v226
	v_mov_b32_e32 v248, v225
	v_mov_b32_e32 v249, v227
	v_pk_mul_f32 v[212:213], v[100:101], v[172:173]
	v_pk_mul_f32 v[214:215], v[100:101], v[170:171]
	v_pk_mul_f32 v[216:217], v[102:103], v[176:177]
	v_pk_mul_f32 v[218:219], v[102:103], v[174:175]
	v_pk_mul_f32 v[220:221], v[96:97], v[180:181]
	v_pk_mul_f32 v[222:223], v[96:97], v[178:179]
	v_pk_mul_f32 v[224:225], v[98:99], v[248:249]
	v_pk_mul_f32 v[226:227], v[98:99], v[182:183]
	v_pk_fma_f32 v[212:213], v[108:109], v[170:171], v[212:213] neg_lo:[0,0,1] neg_hi:[0,0,1]
	v_pk_fma_f32 v[214:215], v[108:109], v[172:173], v[214:215]
	v_pk_fma_f32 v[216:217], v[110:111], v[174:175], v[216:217] neg_lo:[0,0,1] neg_hi:[0,0,1]
	v_pk_fma_f32 v[218:219], v[110:111], v[176:177], v[218:219]
	v_pk_fma_f32 v[220:221], v[104:105], v[178:179], v[220:221] neg_lo:[0,0,1] neg_hi:[0,0,1]
	v_pk_fma_f32 v[222:223], v[104:105], v[180:181], v[222:223]
	v_pk_fma_f32 v[224:225], v[106:107], v[182:183], v[224:225] neg_lo:[0,0,1] neg_hi:[0,0,1]
	v_pk_fma_f32 v[226:227], v[106:107], v[248:249], v[226:227]
	v_pk_mul_f32 v[212:213], v[152:153], v[212:213] op_sel_hi:[0,1]
	v_pk_mul_f32 v[214:215], v[152:153], v[214:215] op_sel_hi:[0,1]
	v_pk_mul_f32 v[216:217], v[152:153], v[216:217] op_sel_hi:[0,1]
	v_pk_mul_f32 v[218:219], v[152:153], v[218:219] op_sel_hi:[0,1]
	v_pk_mul_f32 v[220:221], v[152:153], v[220:221] op_sel_hi:[0,1]
	v_pk_mul_f32 v[222:223], v[152:153], v[222:223] op_sel_hi:[0,1]
	v_pk_mul_f32 v[224:225], v[152:153], v[224:225] op_sel_hi:[0,1]
	v_pk_mul_f32 v[226:227], v[152:153], v[226:227] op_sel_hi:[0,1]
	v_cvt_pk_bf16_f32 v170, v212, v213
	v_cvt_pk_bf16_f32 v171, v216, v217
	v_cvt_pk_bf16_f32 v172, v220, v221
	v_cvt_pk_bf16_f32 v173, v224, v225
	v_cvt_pk_bf16_f32 v174, v214, v215
	v_cvt_pk_bf16_f32 v175, v218, v219
	v_cvt_pk_bf16_f32 v176, v222, v223
	v_cvt_pk_bf16_f32 v177, v226, v227
	global_store_dwordx4 v169, v[170:173], s[22:23]
	global_store_dwordx4 v169, v[174:177], s[22:23] offset:64
	v_add_u32_e32 v245, 0x9000, v128
	global_load_dwordx4 v[212:215], v245, s[26:27]
	global_load_dwordx4 v[216:219], v245, s[26:27] offset:16
	global_load_dwordx4 v[220:223], v245, s[26:27] offset:32
	global_load_dwordx4 v[224:227], v245, s[26:27] offset:48
	v_add_f32_e32 v152, 0x42000000, v129
	v_mul_f32_e32 v152, s2, v152
	v_exp_f32_e32 v152, v152
	v_add_u32_e32 v168, 0x70000, v131
	s_waitcnt vmcnt(12)
	v_mov_b32_e32 v170, v228
	v_mov_b32_e32 v171, v230
	v_mov_b32_e32 v172, v229
	v_mov_b32_e32 v173, v231
	v_mov_b32_e32 v174, v232
	v_mov_b32_e32 v175, v234
	v_mov_b32_e32 v176, v233
	v_mov_b32_e32 v177, v235
	v_mov_b32_e32 v178, v236
	v_mov_b32_e32 v179, v238
	v_mov_b32_e32 v180, v237
	v_mov_b32_e32 v181, v239
	v_mov_b32_e32 v182, v240
	v_mov_b32_e32 v183, v242
	v_mov_b32_e32 v248, v241
	v_mov_b32_e32 v249, v243
	v_pk_mul_f32 v[228:229], v[84:85], v[172:173]
	v_pk_mul_f32 v[230:231], v[84:85], v[170:171]
	v_pk_mul_f32 v[232:233], v[86:87], v[176:177]
	v_pk_mul_f32 v[234:235], v[86:87], v[174:175]
	v_pk_mul_f32 v[236:237], v[80:81], v[180:181]
	v_pk_mul_f32 v[238:239], v[80:81], v[178:179]
	v_pk_mul_f32 v[240:241], v[82:83], v[248:249]
	v_pk_mul_f32 v[242:243], v[82:83], v[182:183]
	v_pk_fma_f32 v[228:229], v[92:93], v[170:171], v[228:229] neg_lo:[0,0,1] neg_hi:[0,0,1]
	v_pk_fma_f32 v[230:231], v[92:93], v[172:173], v[230:231]
	v_pk_fma_f32 v[232:233], v[94:95], v[174:175], v[232:233] neg_lo:[0,0,1] neg_hi:[0,0,1]
	v_pk_fma_f32 v[234:235], v[94:95], v[176:177], v[234:235]
	v_pk_fma_f32 v[236:237], v[88:89], v[178:179], v[236:237] neg_lo:[0,0,1] neg_hi:[0,0,1]
	v_pk_fma_f32 v[238:239], v[88:89], v[180:181], v[238:239]
	v_pk_fma_f32 v[240:241], v[90:91], v[182:183], v[240:241] neg_lo:[0,0,1] neg_hi:[0,0,1]
	v_pk_fma_f32 v[242:243], v[90:91], v[248:249], v[242:243]
	v_pk_mul_f32 v[228:229], v[152:153], v[228:229] op_sel_hi:[0,1]
	v_pk_mul_f32 v[230:231], v[152:153], v[230:231] op_sel_hi:[0,1]
	v_pk_mul_f32 v[232:233], v[152:153], v[232:233] op_sel_hi:[0,1]
	v_pk_mul_f32 v[234:235], v[152:153], v[234:235] op_sel_hi:[0,1]
	v_pk_mul_f32 v[236:237], v[152:153], v[236:237] op_sel_hi:[0,1]
	v_pk_mul_f32 v[238:239], v[152:153], v[238:239] op_sel_hi:[0,1]
	v_pk_mul_f32 v[240:241], v[152:153], v[240:241] op_sel_hi:[0,1]
	v_pk_mul_f32 v[242:243], v[152:153], v[242:243] op_sel_hi:[0,1]
	v_cvt_pk_bf16_f32 v170, v228, v229
	v_cvt_pk_bf16_f32 v171, v232, v233
	v_cvt_pk_bf16_f32 v172, v236, v237
	v_cvt_pk_bf16_f32 v173, v240, v241
	v_cvt_pk_bf16_f32 v174, v230, v231
	v_cvt_pk_bf16_f32 v175, v234, v235
	v_cvt_pk_bf16_f32 v176, v238, v239
	v_cvt_pk_bf16_f32 v177, v242, v243
	global_store_dwordx4 v168, v[170:173], s[22:23]
	global_store_dwordx4 v168, v[174:177], s[22:23] offset:64
	v_add_u32_e32 v246, 0xa000, v128
	global_load_dwordx4 v[228:231], v246, s[26:27]
	global_load_dwordx4 v[232:235], v246, s[26:27] offset:16
	global_load_dwordx4 v[236:239], v246, s[26:27] offset:32
	global_load_dwordx4 v[240:243], v246, s[26:27] offset:48
	v_add_f32_e32 v152, 0x42400000, v129
	v_mul_f32_e32 v152, s2, v152
	v_exp_f32_e32 v152, v152
	v_add_u32_e32 v169, 0xa8000, v131
	s_waitcnt vmcnt(12)
; __device__ __forceinline__ u32x4 pack8(const float (&v)[8]) { u32x4 w; w.x = cvtpk(v[0], v[1]); w.y = cvtpk(v[2], v[3]); w.z = cvtpk(v[4], v[5]); w.w = cvtpk(v[6], v[7]); return w; }
;     template <int TYPE> __device__ __forceinline__ void run(const Acc& acc, const Unit& u, int wr, int wc, int fr, int fq) const {
;     ...
;                 if (TYPE == 0 || TYPE == 1) {
;                     const int pos = row & (SEQ - 1);
;                     const f32x4* tp = (const f32x4*)(tab + ((size_t)pos * 32 + 8 * fq) * 2);
;                     const float lgp = lg2gamma(((u.pn & 1) << 2) + wc) * (float)pos;
;                     const float sc = (TYPE == 1) ? 0.125f * __builtin_amdgcn_exp2f(-lgp) : __builtin_amdgcn_exp2f(lgp);
; #pragma unroll
;                     for (int jj = 0; jj < 4; ++jj) { const f32x4 cs = tp[jj];
;                         { const float t1 = v[0][2 * jj], t2 = v[1][2 * jj]; v[0][2 * jj] = (t1 * cs.x - t2 * cs.y) * sc; v[1][2 * jj] = (t1 * cs.y + t2 * cs.x) * sc; }
;                         { const float t1 = v[0][2 * jj + 1], t2 = v[1][2 * jj + 1]; v[0][2 * jj + 1] = (t1 * cs.z - t2 * cs.w) * sc; v[1][2 * jj + 1] = (t1 * cs.w + t2 * cs.z) * sc; } }
;                 }
;     ...
;                 bf16_t* rowp = Z + (size_t)row * DIN + colbase;
;                 *(u32x4*)(rowp) = pack8(v[0]); *(u32x4*)(rowp + 32) = pack8(v[1]);
	v_mov_b32_e32 v170, v186
	v_mov_b32_e32 v171, v188
	v_mov_b32_e32 v172, v187
	v_mov_b32_e32 v173, v189
	v_mov_b32_e32 v174, v190
	v_mov_b32_e32 v175, v192
	v_mov_b32_e32 v176, v191
	v_mov_b32_e32 v177, v193
	v_mov_b32_e32 v178, v194
	v_mov_b32_e32 v179, v196
	v_mov_b32_e32 v180, v195
	v_mov_b32_e32 v181, v197
	v_mov_b32_e32 v182, v198
	v_mov_b32_e32 v183, v200
	v_mov_b32_e32 v248, v199
	v_mov_b32_e32 v249, v201
	v_pk_mul_f32 v[186:187], v[68:69], v[172:173]
	v_pk_mul_f32 v[188:189], v[68:69], v[170:171]
	v_pk_mul_f32 v[190:191], v[70:71], v[176:177]
	v_pk_mul_f32 v[192:193], v[70:71], v[174:175]
	v_pk_mul_f32 v[194:195], v[64:65], v[180:181]
	v_pk_mul_f32 v[196:197], v[64:65], v[178:179]
	v_pk_mul_f32 v[198:199], v[66:67], v[248:249]
	v_pk_mul_f32 v[200:201], v[66:67], v[182:183]
	v_pk_fma_f32 v[186:187], v[76:77], v[170:171], v[186:187] neg_lo:[0,0,1] neg_hi:[0,0,1]
	v_pk_fma_f32 v[188:189], v[76:77], v[172:173], v[188:189]
	v_pk_fma_f32 v[190:191], v[78:79], v[174:175], v[190:191] neg_lo:[0,0,1] neg_hi:[0,0,1]
	v_pk_fma_f32 v[192:193], v[78:79], v[176:177], v[192:193]
	v_pk_fma_f32 v[194:195], v[72:73], v[178:179], v[194:195] neg_lo:[0,0,1] neg_hi:[0,0,1]
	v_pk_fma_f32 v[196:197], v[72:73], v[180:181], v[196:197]
	v_pk_fma_f32 v[198:199], v[74:75], v[182:183], v[198:199] neg_lo:[0,0,1] neg_hi:[0,0,1]
	v_pk_fma_f32 v[200:201], v[74:75], v[248:249], v[200:201]
	v_pk_mul_f32 v[186:187], v[152:153], v[186:187] op_sel_hi:[0,1]
	v_pk_mul_f32 v[188:189], v[152:153], v[188:189] op_sel_hi:[0,1]
	v_pk_mul_f32 v[190:191], v[152:153], v[190:191] op_sel_hi:[0,1]
	v_pk_mul_f32 v[192:193], v[152:153], v[192:193] op_sel_hi:[0,1]
	v_pk_mul_f32 v[194:195], v[152:153], v[194:195] op_sel_hi:[0,1]
	v_pk_mul_f32 v[196:197], v[152:153], v[196:197] op_sel_hi:[0,1]
	v_pk_mul_f32 v[198:199], v[152:153], v[198:199] op_sel_hi:[0,1]
	v_pk_mul_f32 v[200:201], v[152:153], v[200:201] op_sel_hi:[0,1]
	v_cvt_pk_bf16_f32 v170, v186, v187
	v_cvt_pk_bf16_f32 v171, v190, v191
	v_cvt_pk_bf16_f32 v172, v194, v195
	v_cvt_pk_bf16_f32 v173, v198, v199
	v_cvt_pk_bf16_f32 v174, v188, v189
	v_cvt_pk_bf16_f32 v175, v192, v193
	v_cvt_pk_bf16_f32 v176, v196, v197
	v_cvt_pk_bf16_f32 v177, v200, v201
	global_store_dwordx4 v169, v[170:173], s[22:23]
	global_store_dwordx4 v169, v[174:177], s[22:23] offset:64
	v_add_u32_e32 v247, 0xb000, v128
	global_load_dwordx4 v[186:189], v247, s[26:27]
	global_load_dwordx4 v[190:193], v247, s[26:27] offset:16
	global_load_dwordx4 v[194:197], v247, s[26:27] offset:32
	global_load_dwordx4 v[198:201], v247, s[26:27] offset:48
	v_add_f32_e32 v152, 0x43000000, v129
	v_mul_f32_e32 v152, s2, v152
	v_exp_f32_e32 v152, v152
	v_add_u32_e32 v168, 0x1c0000, v131
	s_waitcnt vmcnt(12)
	v_mov_b32_e32 v170, v132
	v_mov_b32_e32 v171, v134
	v_mov_b32_e32 v172, v133
	v_mov_b32_e32 v173, v135
	v_mov_b32_e32 v174, v136
	v_mov_b32_e32 v175, v138
	v_mov_b32_e32 v176, v137
	v_mov_b32_e32 v177, v139
	v_mov_b32_e32 v178, v140
	v_mov_b32_e32 v179, v142
	v_mov_b32_e32 v180, v141
	v_mov_b32_e32 v181, v143
	v_mov_b32_e32 v182, v164
	v_mov_b32_e32 v183, v166
	v_mov_b32_e32 v248, v165
	v_mov_b32_e32 v249, v167
	v_pk_mul_f32 v[132:133], v[52:53], v[172:173]
	v_pk_mul_f32 v[134:135], v[52:53], v[170:171]
	v_pk_mul_f32 v[136:137], v[54:55], v[176:177]
	v_pk_mul_f32 v[138:139], v[54:55], v[174:175]
	v_pk_mul_f32 v[140:141], v[48:49], v[180:181]
	v_pk_mul_f32 v[142:143], v[48:49], v[178:179]
	v_pk_mul_f32 v[164:165], v[50:51], v[248:249]
	v_pk_mul_f32 v[166:167], v[50:51], v[182:183]
	v_pk_fma_f32 v[132:133], v[60:61], v[170:171], v[132:133] neg_lo:[0,0,1] neg_hi:[0,0,1]
	v_pk_fma_f32 v[134:135], v[60:61], v[172:173], v[134:135]
	v_pk_fma_f32 v[136:137], v[62:63], v[174:175], v[136:137] neg_lo:[0,0,1] neg_hi:[0,0,1]
	v_pk_fma_f32 v[138:139], v[62:63], v[176:177], v[138:139]
	v_pk_fma_f32 v[140:141], v[56:57], v[178:179], v[140:141] neg_lo:[0,0,1] neg_hi:[0,0,1]
	v_pk_fma_f32 v[142:143], v[56:57], v[180:181], v[142:143]
	v_pk_fma_f32 v[164:165], v[58:59], v[182:183], v[164:165] neg_lo:[0,0,1] neg_hi:[0,0,1]
	v_pk_fma_f32 v[166:167], v[58:59], v[248:249], v[166:167]
	v_pk_mul_f32 v[132:133], v[152:153], v[132:133] op_sel_hi:[0,1]
	v_pk_mul_f32 v[134:135], v[152:153], v[134:135] op_sel_hi:[0,1]
	v_pk_mul_f32 v[136:137], v[152:153], v[136:137] op_sel_hi:[0,1]
	v_pk_mul_f32 v[138:139], v[152:153], v[138:139] op_sel_hi:[0,1]
	v_pk_mul_f32 v[140:141], v[152:153], v[140:141] op_sel_hi:[0,1]
	v_pk_mul_f32 v[142:143], v[152:153], v[142:143] op_sel_hi:[0,1]
	v_pk_mul_f32 v[164:165], v[152:153], v[164:165] op_sel_hi:[0,1]
	v_pk_mul_f32 v[166:167], v[152:153], v[166:167] op_sel_hi:[0,1]
	v_cvt_pk_bf16_f32 v170, v132, v133
	v_cvt_pk_bf16_f32 v171, v136, v137
	v_cvt_pk_bf16_f32 v172, v140, v141
	v_cvt_pk_bf16_f32 v173, v164, v165
	v_cvt_pk_bf16_f32 v174, v134, v135
	v_cvt_pk_bf16_f32 v175, v138, v139
	v_cvt_pk_bf16_f32 v176, v142, v143
	v_cvt_pk_bf16_f32 v177, v166, v167
	global_store_dwordx4 v168, v[170:173], s[22:23]
	global_store_dwordx4 v168, v[174:177], s[22:23] offset:64
	v_add_f32_e32 v152, 0x43100000, v129
	v_mul_f32_e32 v152, s2, v152
	v_exp_f32_e32 v152, v152
	v_add_u32_e32 v169, 0x1f8000, v131
	s_waitcnt vmcnt(8)
; __device__ __forceinline__ u32x4 pack8(const float (&v)[8]) { u32x4 w; w.x = cvtpk(v[0], v[1]); w.y = cvtpk(v[2], v[3]); w.z = cvtpk(v[4], v[5]); w.w = cvtpk(v[6], v[7]); return w; }
;     template <int TYPE> __device__ __forceinline__ void run(const Acc& acc, const Unit& u, int wr, int wc, int fr, int fq) const {
;     ...
;                 if (TYPE == 0 || TYPE == 1) {
;                     const int pos = row & (SEQ - 1);
;                     const f32x4* tp = (const f32x4*)(tab + ((size_t)pos * 32 + 8 * fq) * 2);
;                     const float lgp = lg2gamma(((u.pn & 1) << 2) + wc) * (float)pos;
;                     const float sc = (TYPE == 1) ? 0.125f * __builtin_amdgcn_exp2f(-lgp) : __builtin_amdgcn_exp2f(lgp);
; #pragma unroll
;                     for (int jj = 0; jj < 4; ++jj) { const f32x4 cs = tp[jj];
;                         { const float t1 = v[0][2 * jj], t2 = v[1][2 * jj]; v[0][2 * jj] = (t1 * cs.x - t2 * cs.y) * sc; v[1][2 * jj] = (t1 * cs.y + t2 * cs.x) * sc; }
;                         { const float t1 = v[0][2 * jj + 1], t2 = v[1][2 * jj + 1]; v[0][2 * jj + 1] = (t1 * cs.z - t2 * cs.w) * sc; v[1][2 * jj + 1] = (t1 * cs.w + t2 * cs.z) * sc; } }
;                 }
;     ...
;                 bf16_t* rowp = Z + (size_t)row * DIN + colbase;
;                 *(u32x4*)(rowp) = pack8(v[0]); *(u32x4*)(rowp + 32) = pack8(v[1]);
	v_mov_b32_e32 v170, v212
	v_mov_b32_e32 v171, v214
	v_mov_b32_e32 v172, v213
	v_mov_b32_e32 v173, v215
	v_mov_b32_e32 v174, v216
	v_mov_b32_e32 v175, v218
	v_mov_b32_e32 v176, v217
	v_mov_b32_e32 v177, v219
	v_mov_b32_e32 v178, v220
	v_mov_b32_e32 v179, v222
	v_mov_b32_e32 v180, v221
	v_mov_b32_e32 v181, v223
	v_mov_b32_e32 v182, v224
	v_mov_b32_e32 v183, v226
	v_mov_b32_e32 v248, v225
	v_mov_b32_e32 v249, v227
	v_pk_mul_f32 v[212:213], v[36:37], v[172:173]
	v_pk_mul_f32 v[214:215], v[36:37], v[170:171]
	v_pk_mul_f32 v[216:217], v[38:39], v[176:177]
	v_pk_mul_f32 v[218:219], v[38:39], v[174:175]
	v_pk_mul_f32 v[220:221], v[32:33], v[180:181]
	v_pk_mul_f32 v[222:223], v[32:33], v[178:179]
	v_pk_mul_f32 v[224:225], v[34:35], v[248:249]
	v_pk_mul_f32 v[226:227], v[34:35], v[182:183]
	v_pk_fma_f32 v[212:213], v[44:45], v[170:171], v[212:213] neg_lo:[0,0,1] neg_hi:[0,0,1]
	v_pk_fma_f32 v[214:215], v[44:45], v[172:173], v[214:215]
	v_pk_fma_f32 v[216:217], v[46:47], v[174:175], v[216:217] neg_lo:[0,0,1] neg_hi:[0,0,1]
	v_pk_fma_f32 v[218:219], v[46:47], v[176:177], v[218:219]
	v_pk_fma_f32 v[220:221], v[40:41], v[178:179], v[220:221] neg_lo:[0,0,1] neg_hi:[0,0,1]
	v_pk_fma_f32 v[222:223], v[40:41], v[180:181], v[222:223]
	v_pk_fma_f32 v[224:225], v[42:43], v[182:183], v[224:225] neg_lo:[0,0,1] neg_hi:[0,0,1]
	v_pk_fma_f32 v[226:227], v[42:43], v[248:249], v[226:227]
	v_pk_mul_f32 v[212:213], v[152:153], v[212:213] op_sel_hi:[0,1]
	v_pk_mul_f32 v[214:215], v[152:153], v[214:215] op_sel_hi:[0,1]
	v_pk_mul_f32 v[216:217], v[152:153], v[216:217] op_sel_hi:[0,1]
	v_pk_mul_f32 v[218:219], v[152:153], v[218:219] op_sel_hi:[0,1]
	v_pk_mul_f32 v[220:221], v[152:153], v[220:221] op_sel_hi:[0,1]
	v_pk_mul_f32 v[222:223], v[152:153], v[222:223] op_sel_hi:[0,1]
	v_pk_mul_f32 v[224:225], v[152:153], v[224:225] op_sel_hi:[0,1]
	v_pk_mul_f32 v[226:227], v[152:153], v[226:227] op_sel_hi:[0,1]
	v_cvt_pk_bf16_f32 v170, v212, v213
	v_cvt_pk_bf16_f32 v171, v216, v217
	v_cvt_pk_bf16_f32 v172, v220, v221
	v_cvt_pk_bf16_f32 v173, v224, v225
	v_cvt_pk_bf16_f32 v174, v214, v215
	v_cvt_pk_bf16_f32 v175, v218, v219
	v_cvt_pk_bf16_f32 v176, v222, v223
	v_cvt_pk_bf16_f32 v177, v226, v227
	global_store_dwordx4 v169, v[170:173], s[22:23]
	global_store_dwordx4 v169, v[174:177], s[22:23] offset:64
	v_add_f32_e32 v152, 0x43200000, v129
	v_mul_f32_e32 v152, s2, v152
	v_exp_f32_e32 v152, v152
	v_add_u32_e32 v168, 0x230000, v131
	s_waitcnt vmcnt(4)
; __device__ __forceinline__ u32x4 pack8(const float (&v)[8]) { u32x4 w; w.x = cvtpk(v[0], v[1]); w.y = cvtpk(v[2], v[3]); w.z = cvtpk(v[4], v[5]); w.w = cvtpk(v[6], v[7]); return w; }
;     template <int TYPE> __device__ __forceinline__ void run(const Acc& acc, const Unit& u, int wr, int wc, int fr, int fq) const {
;     ...
;                 if (TYPE == 0 || TYPE == 1) {
;                     const int pos = row & (SEQ - 1);
;                     const f32x4* tp = (const f32x4*)(tab + ((size_t)pos * 32 + 8 * fq) * 2);
;                     const float lgp = lg2gamma(((u.pn & 1) << 2) + wc) * (float)pos;
;                     const float sc = (TYPE == 1) ? 0.125f * __builtin_amdgcn_exp2f(-lgp) : __builtin_amdgcn_exp2f(lgp);
; #pragma unroll
;                     for (int jj = 0; jj < 4; ++jj) { const f32x4 cs = tp[jj];
;                         { const float t1 = v[0][2 * jj], t2 = v[1][2 * jj]; v[0][2 * jj] = (t1 * cs.x - t2 * cs.y) * sc; v[1][2 * jj] = (t1 * cs.y + t2 * cs.x) * sc; }
;                         { const float t1 = v[0][2 * jj + 1], t2 = v[1][2 * jj + 1]; v[0][2 * jj + 1] = (t1 * cs.z - t2 * cs.w) * sc; v[1][2 * jj + 1] = (t1 * cs.w + t2 * cs.z) * sc; } }
;                 }
;     ...
;                 bf16_t* rowp = Z + (size_t)row * DIN + colbase;
;                 *(u32x4*)(rowp) = pack8(v[0]); *(u32x4*)(rowp + 32) = pack8(v[1]);
	v_mov_b32_e32 v170, v228
	v_mov_b32_e32 v171, v230
	v_mov_b32_e32 v172, v229
	v_mov_b32_e32 v173, v231
	v_mov_b32_e32 v174, v232
	v_mov_b32_e32 v175, v234
	v_mov_b32_e32 v176, v233
	v_mov_b32_e32 v177, v235
	v_mov_b32_e32 v178, v236
	v_mov_b32_e32 v179, v238
	v_mov_b32_e32 v180, v237
	v_mov_b32_e32 v181, v239
	v_mov_b32_e32 v182, v240
	v_mov_b32_e32 v183, v242
	v_mov_b32_e32 v248, v241
	v_mov_b32_e32 v249, v243
	v_pk_mul_f32 v[228:229], v[20:21], v[172:173]
	v_pk_mul_f32 v[230:231], v[20:21], v[170:171]
	v_pk_mul_f32 v[232:233], v[22:23], v[176:177]
	v_pk_mul_f32 v[234:235], v[22:23], v[174:175]
	v_pk_mul_f32 v[236:237], v[16:17], v[180:181]
	v_pk_mul_f32 v[238:239], v[16:17], v[178:179]
	v_pk_mul_f32 v[240:241], v[18:19], v[248:249]
	v_pk_mul_f32 v[242:243], v[18:19], v[182:183]
	v_pk_fma_f32 v[228:229], v[28:29], v[170:171], v[228:229] neg_lo:[0,0,1] neg_hi:[0,0,1]
	v_pk_fma_f32 v[230:231], v[28:29], v[172:173], v[230:231]
	v_pk_fma_f32 v[232:233], v[30:31], v[174:175], v[232:233] neg_lo:[0,0,1] neg_hi:[0,0,1]
	v_pk_fma_f32 v[234:235], v[30:31], v[176:177], v[234:235]
	v_pk_fma_f32 v[236:237], v[24:25], v[178:179], v[236:237] neg_lo:[0,0,1] neg_hi:[0,0,1]
	v_pk_fma_f32 v[238:239], v[24:25], v[180:181], v[238:239]
	v_pk_fma_f32 v[240:241], v[26:27], v[182:183], v[240:241] neg_lo:[0,0,1] neg_hi:[0,0,1]
	v_pk_fma_f32 v[242:243], v[26:27], v[248:249], v[242:243]
	v_pk_mul_f32 v[228:229], v[152:153], v[228:229] op_sel_hi:[0,1]
	v_pk_mul_f32 v[230:231], v[152:153], v[230:231] op_sel_hi:[0,1]
	v_pk_mul_f32 v[232:233], v[152:153], v[232:233] op_sel_hi:[0,1]
	v_pk_mul_f32 v[234:235], v[152:153], v[234:235] op_sel_hi:[0,1]
	v_pk_mul_f32 v[236:237], v[152:153], v[236:237] op_sel_hi:[0,1]
	v_pk_mul_f32 v[238:239], v[152:153], v[238:239] op_sel_hi:[0,1]
	v_pk_mul_f32 v[240:241], v[152:153], v[240:241] op_sel_hi:[0,1]
	v_pk_mul_f32 v[242:243], v[152:153], v[242:243] op_sel_hi:[0,1]
	v_cvt_pk_bf16_f32 v170, v228, v229
	v_cvt_pk_bf16_f32 v171, v232, v233
	v_cvt_pk_bf16_f32 v172, v236, v237
	v_cvt_pk_bf16_f32 v173, v240, v241
	v_cvt_pk_bf16_f32 v174, v230, v231
	v_cvt_pk_bf16_f32 v175, v234, v235
	v_cvt_pk_bf16_f32 v176, v238, v239
	v_cvt_pk_bf16_f32 v177, v242, v243
	global_store_dwordx4 v168, v[170:173], s[22:23]
	global_store_dwordx4 v168, v[174:177], s[22:23] offset:64
	v_add_f32_e32 v152, 0x43300000, v129
	v_mul_f32_e32 v152, s2, v152
	v_exp_f32_e32 v152, v152
	v_add_u32_e32 v169, 0x268000, v131
	s_waitcnt vmcnt(0)
	v_mov_b32_e32 v170, v186
	v_mov_b32_e32 v171, v188
	v_mov_b32_e32 v172, v187
	v_mov_b32_e32 v173, v189
	v_mov_b32_e32 v174, v190
	v_mov_b32_e32 v175, v192
	v_mov_b32_e32 v176, v191
	v_mov_b32_e32 v177, v193
	v_mov_b32_e32 v178, v194
	v_mov_b32_e32 v179, v196
	v_mov_b32_e32 v180, v195
	v_mov_b32_e32 v181, v197
	v_mov_b32_e32 v182, v198
	v_mov_b32_e32 v183, v200
	v_mov_b32_e32 v248, v199
	v_mov_b32_e32 v249, v201
	v_pk_mul_f32 v[186:187], v[4:5], v[172:173]
	v_pk_mul_f32 v[188:189], v[4:5], v[170:171]
	v_pk_mul_f32 v[190:191], v[6:7], v[176:177]
	v_pk_mul_f32 v[192:193], v[6:7], v[174:175]
	v_pk_mul_f32 v[194:195], v[0:1], v[180:181]
	v_pk_mul_f32 v[196:197], v[0:1], v[178:179]
	v_pk_mul_f32 v[198:199], v[2:3], v[248:249]
	v_pk_mul_f32 v[200:201], v[2:3], v[182:183]
	v_pk_fma_f32 v[186:187], v[12:13], v[170:171], v[186:187] neg_lo:[0,0,1] neg_hi:[0,0,1]
	v_pk_fma_f32 v[188:189], v[12:13], v[172:173], v[188:189]
	v_pk_fma_f32 v[190:191], v[14:15], v[174:175], v[190:191] neg_lo:[0,0,1] neg_hi:[0,0,1]
	v_pk_fma_f32 v[192:193], v[14:15], v[176:177], v[192:193]
	v_pk_fma_f32 v[194:195], v[8:9], v[178:179], v[194:195] neg_lo:[0,0,1] neg_hi:[0,0,1]
	v_pk_fma_f32 v[196:197], v[8:9], v[180:181], v[196:197]
	v_pk_fma_f32 v[198:199], v[10:11], v[182:183], v[198:199] neg_lo:[0,0,1] neg_hi:[0,0,1]
	v_pk_fma_f32 v[200:201], v[10:11], v[248:249], v[200:201]
	v_pk_mul_f32 v[186:187], v[152:153], v[186:187] op_sel_hi:[0,1]
	v_pk_mul_f32 v[188:189], v[152:153], v[188:189] op_sel_hi:[0,1]
	v_pk_mul_f32 v[190:191], v[152:153], v[190:191] op_sel_hi:[0,1]
	v_pk_mul_f32 v[192:193], v[152:153], v[192:193] op_sel_hi:[0,1]
	v_pk_mul_f32 v[194:195], v[152:153], v[194:195] op_sel_hi:[0,1]
	v_pk_mul_f32 v[196:197], v[152:153], v[196:197] op_sel_hi:[0,1]
	v_pk_mul_f32 v[198:199], v[152:153], v[198:199] op_sel_hi:[0,1]
	v_pk_mul_f32 v[200:201], v[152:153], v[200:201] op_sel_hi:[0,1]
	v_cvt_pk_bf16_f32 v170, v186, v187
	v_cvt_pk_bf16_f32 v171, v190, v191
	v_cvt_pk_bf16_f32 v172, v194, v195
	v_cvt_pk_bf16_f32 v173, v198, v199
	v_cvt_pk_bf16_f32 v174, v188, v189
	v_cvt_pk_bf16_f32 v175, v192, v193
	v_cvt_pk_bf16_f32 v176, v196, v197
	v_cvt_pk_bf16_f32 v177, v200, v201
	global_store_dwordx4 v169, v[170:173], s[22:23]
	global_store_dwordx4 v169, v[174:177], s[22:23] offset:64
	s_andn2_b64 vcc, exec, s[4:5]
	s_mov_b64 s[2:3], -1
	s_branch .Lz_epi_done

; __device__ __forceinline__ int lane_id() { return (int)__builtin_amdgcn_mbcnt_hi(~0u, __builtin_amdgcn_mbcnt_lo(~0u, 0u)); }
; #define PG8_BAR __builtin_amdgcn_s_barrier()
; template <class Epi, bool ALIGN_EPI>
; __device__ __forceinline__ void gemm_phase(LAS unsigned char* lds, const Gemm g, const StaticOrder& S, const Epi& E, const int wid) {
;     ...
;         if constexpr (ALIGN_EPI) { if (wr == 0) PG8_BAR; }
;         { int l2 = lane_id(); asm volatile("" : "+v"(l2)); E(acc, cur, wr, wc, l2 & 15, (l2 >> 4) & 3); }
;         if (!has_next) break;
; #pragma unroll
;         for (int a = 0; a < 2; ++a)
; #pragma unroll
;             for (int b = 0; b < 2; ++b)
; #pragma unroll
;                 for (int m = 0; m < 4; ++m)
; #pragma unroll
;                     for (int n = 0; n < 2; ++n) acc[a][b][m][n] = (f32x4){0.f, 0.f, 0.f, 0.f};
;         cur = nxt; cA = nA; cB = nB; ++ui;
;         if constexpr (ALIGN_EPI) { if (wr == 1) PG8_BAR; }
.Lz_epi_done:
	s_cbranch_vccnz .LBB0_101
	s_and_b64 vcc, exec, s[0:1]
	s_cbranch_vccnz .LBB0_100
	s_barrier
	s_branch .LBB0_100
